# out-proj GEMM: split-K factor of the tail tiles 8 -> 4 (half the atomic-add volume, 16 instead of 32 tail units per XCD)
# speedup vs baseline: 1.0078x; 1.0009x over previous
; DI int TID() { int t = threadIdx.x; asm volatile("" : "+v"(t)); return t; }
; DI int BID() { int t = blockIdx.x; asm volatile("" : "+s"(t)); return t; }
;   constexpr int BN = 128 * WM, GBUF = (256 + BN) * GSTR;
;   const int tid = TID(), lane = tid & 63, wv = tid >> 6, l31 = lane & 31, hh = lane >> 5;
;   const int wm = (WM == 1) ? wv : (wv & 3), wn = (WM == 1) ? 0 : (wv >> 2);
;   const int xcd = BID() & 7, slot = BID() >> 3, nslots = gridDim.x >> 3;
;   const int nk = K >> 6;
;   const int tiles_x = ((MT - xcd + 7) >> 3) * ntiles;
;   constexpr int NSP = NSPLIT > 0 ? NSPLIT : 1;
;   const int full = NSPLIT > 0 ? (tiles_x / nslots) * nslots : tiles_x;
;   const int nunits = full + (tiles_x - full) * NSP;
;   for (int u = slot; u < nunits; u += nslots) {
;     const bool part = u >= full;
;     const int q = part ? full + (u - full) / NSP : u, ks = part ? (u - full) % NSP : 0;
;     const int mtl = q / ntiles, nt = q - mtl * ntiles, mt = mtl * 8 + xcd;
;     if (skipctx && (mt % PT) == 0) continue;
;     const int kt0 = part ? (ks * nk) / NSP : 0, kt1 = part ? ((ks + 1) * nk) / NSP : nk;
;     const bf16_t* Ag = A + (size_t)mt * 256 * K;
;     const bf16_t* Wg = W + (size_t)nt * BN * K;
;     f32x16 acc[WM][4];
; #pragma unroll
;     for (int mi = 0; mi < WM; ++mi)
; #pragma unroll
;       for (int nb = 0; nb < 4; ++nb)
; #pragma unroll
;         for (int i = 0; i < 16; ++i) acc[mi][nb][i] = 0.f;
;     uint4 ra0, ra1, ra2, ra3, rw0, rw1, rw2, rw3;
;     rw2 = make_uint4(0, 0, 0, 0); rw3 = rw2;
;     const int grow = tid >> 3, gcol = (tid & 7) * 8;
;     const bf16_t* ap = Ag + (size_t)grow * K + gcol;
;     const bf16_t* wp = Wg + (size_t)grow * K + gcol;
;     const int lo = grow * GSTR + (tid & 7) * 16;
.LBB0_94:
	s_andn2_b64 vcc, exec, s[0:1]
	s_cbranch_vccnz .LBB0_133
	s_cmp_gt_i32 s9, 4
	s_mov_b64 s[0:1], -1
	s_cbranch_scc0 .LBB0_120
	s_waitcnt vmcnt(1)
	v_mov_b32_e32 v0, v167
	s_mov_b32 s0, s50
	s_and_b32 s3, s0, 7
	s_mov_b32 s0, s50
	s_ashr_i32 s45, s0, 3
	s_sub_i32 s0, 0x8b, s3
	s_lshr_b32 s0, s0, 1
	s_and_b32 s0, s0, 0x44
	v_readlane_b32 s1, v253, 59
	s_mul_hi_u32 s1, s0, s1
	v_readlane_b32 s24, v254, 7
	s_mul_i32 s1, s1, s24
	s_sub_i32 s1, s0, s1
	s_mov_b32 s28, s24
	s_sub_i32 s24, s1, s24
	s_cmp_ge_u32 s1, s28
	s_cselect_b32 s1, s24, s1
	s_sub_i32 s24, s1, s28
	s_cmp_ge_u32 s1, s28
	s_cselect_b32 s1, s24, s1
	s_sub_i32 s46, s0, s1
	s_lshl_b32 s0, s1, 2
	s_add_i32 s47, s46, s0
	s_movk_i32 s34, 0x2000
	s_cmp_ge_i32 s45, s47
	v_readlane_b32 s25, v254, 8
	s_cbranch_scc1 .LBB0_119
	v_readlane_b32 s0, v255, 2
	v_readlane_b32 s1, v255, 3
	s_add_u32 s48, s0, 0x2000
	s_addc_u32 s49, s1, 0
	s_cmp_eq_u32 s12, 1
	s_mov_b32 s0, 0xa00000
	s_cselect_b32 s0, s0, 0x600000
	s_cmp_lg_u32 s12, 0
	s_cselect_b32 s0, s0, 0x3a0000
	v_readlane_b32 s24, v252, 4
	v_ashrrev_i32_e32 v2, 3, v0
	v_readlane_b32 s25, v252, 5
	s_add_u32 s0, s24, s0
	v_ashrrev_i32_e32 v3, 31, v2
	s_addc_u32 s1, s25, 0
	v_lshlrev_b64 v[4:5], 11, v[2:3]
	v_lshl_add_u64 v[6:7], s[76:77], 0, v[4:5]
	v_lshlrev_b32_e32 v1, 4, v0
	v_lshl_add_u64 v[4:5], s[0:1], 0, v[4:5]
	s_movk_i32 s0, 0x90
	v_and_b32_e32 v140, 0x70, v1
	v_mul_lo_u32 v1, v2, s0
	v_add3_u32 v188, 0, v1, v140
	v_and_b32_e32 v1, 0xdf, v0
	v_ashrrev_i32_e32 v169, 8, v0
	v_and_b32_e32 v187, 31, v0
	v_mul_u32_u24_e32 v189, 0x90, v1
	v_lshrrev_b32_e32 v1, 1, v0
	v_and_b32_e32 v190, 16, v1
	v_lshl_or_b32 v1, v169, 7, v187
	v_and_b32_e32 v186, 0xc0, v0
	v_mul_lo_u32 v1, v1, s0
	v_lshlrev_b32_e32 v0, 7, v0
	s_movk_i32 s0, 0x1000
	s_waitcnt vmcnt(0)
	v_lshl_add_u64 v[162:163], v[6:7], 0, v[140:141]
	v_lshl_add_u64 v[164:165], v[4:5], 0, v[140:141]
	v_add_u32_e32 v191, 0x9000, v1
	v_and_or_b32 v168, v0, s0, v187
	s_branch .LBB0_99

; #define SSTOREG(buf_) do { char* b_ = (buf_) + lo; \
;       *(uint4*)(b_) = ra0; *(uint4*)(b_ + 64 * GSTR) = ra1; *(uint4*)(b_ + 128 * GSTR) = ra2; *(uint4*)(b_ + 192 * GSTR) = ra3; \
;       *(uint4*)(b_ + 256 * GSTR) = rw0; *(uint4*)(b_ + 320 * GSTR) = rw1; \
;       if (WM == 2) { *(uint4*)(b_ + 384 * GSTR) = rw2; *(uint4*)(b_ + 448 * GSTR) = rw3; } } while (0)
; #define SSTOREG(buf_) do { char* b_ = (buf_) + lo; \
;       *(uint4*)(b_) = ra0; *(uint4*)(b_ + 64 * GSTR) = ra1; *(uint4*)(b_ + 128 * GSTR) = ra2; *(uint4*)(b_ + 192 * GSTR) = ra3; \
;       *(uint4*)(b_ + 256 * GSTR) = rw0; *(uint4*)(b_ + 320 * GSTR) = rw1; \
;       if (WM == 2) { *(uint4*)(b_ + 384 * GSTR) = rw2; *(uint4*)(b_ + 448 * GSTR) = rw3; } } while (0)
;     ...
;   for (int u = slot; u < nunits; u += nslots) {
;     const bool part = u >= full;
;     const int q = part ? full + (u - full) / NSP : u, ks = part ? (u - full) % NSP : 0;
;     const int mtl = q / ntiles, nt = q - mtl * ntiles, mt = mtl * 8 + xcd;
;     if (skipctx && (mt % PT) == 0) continue;
;     const int kt0 = part ? (ks * nk) / NSP : 0, kt1 = part ? ((ks + 1) * nk) / NSP : nk;
;     const bf16_t* Ag = A + (size_t)mt * 256 * K;
;     const bf16_t* Wg = W + (size_t)nt * BN * K;
;     f32x16 acc[WM][4];
; #pragma unroll
;     for (int mi = 0; mi < WM; ++mi)
; #pragma unroll
;       for (int nb = 0; nb < 4; ++nb)
; #pragma unroll
;         for (int i = 0; i < 16; ++i) acc[mi][nb][i] = 0.f;
;     uint4 ra0, ra1, ra2, ra3, rw0, rw1, rw2, rw3;
;     rw2 = make_uint4(0, 0, 0, 0); rw3 = rw2;
;     const int grow = tid >> 3, gcol = (tid & 7) * 8;
;     const bf16_t* ap = Ag + (size_t)grow * K + gcol;
;     const bf16_t* wp = Wg + (size_t)grow * K + gcol;
;     const int lo = grow * GSTR + (tid & 7) * 16;
;     ...
;     GLOADG(kt0); SSTOREG(smem);
.LBB0_99:
	s_cmp_ge_i32 s45, s46
	s_cselect_b64 s[0:1], -1, 0
	s_sub_i32 s24, s45, s46
	s_lshr_b32 s25, s24, 2
	s_add_i32 s25, s25, s46
	s_cmp_lt_i32 s45, s46
	s_cselect_b64 s[30:31], -1, 0
	s_and_b64 s[28:29], s[30:31], exec
	s_cselect_b32 s25, s45, s25
	s_ashr_i32 s27, s25, 31
	s_lshr_b32 s27, s27, 30
	s_add_i32 s27, s25, s27
	s_ashr_i32 s27, s27, 2
	s_lshl_b32 s28, s27, 3
	s_or_b32 s28, s28, s3
	s_mul_hi_i32 s29, s28, 0x3e0f83e1
	s_lshr_b32 s36, s29, 31
	s_ashr_i32 s29, s29, 3
	s_add_i32 s29, s29, s36
	s_mul_i32 s29, s29, 33
	s_sub_i32 s29, s28, s29
	s_cmp_eq_u32 s29, 0
	s_cselect_b64 s[36:37], -1, 0
	s_and_b64 s[36:37], s[40:41], s[36:37]
	s_and_b64 vcc, exec, s[36:37]
	s_cbranch_vccnz .LBB0_98
	s_lshl_b32 s27, s27, 2
	s_and_b32 s24, s24, 3
	s_sub_i32 s38, s25, s27
	s_lshl_b32 s27, s24, 2
	s_lshl_b32 s24, s24, 4
	s_add_i32 s24, s24, 16
	s_lshr_b32 s36, s24, 2
	s_ashr_i32 s29, s28, 31
	s_ashr_i32 s39, s38, 31
	s_and_b64 s[24:25], s[30:31], exec
	s_cselect_b32 s27, 0, s27
	s_cselect_b32 s30, 16, s36
	s_lshl_b64 s[24:25], s[28:29], 19
	v_lshl_add_u64 v[170:171], v[162:163], 0, s[24:25]
	s_lshl_b64 s[24:25], s[38:39], 19
	v_lshl_add_u64 v[172:173], v[164:165], 0, s[24:25]
	s_mov_b64 s[24:25], 0x20000
	s_lshl_b32 s96, s27, 7
	v_lshl_add_u64 v[174:175], v[170:171], 0, s[24:25]
	s_waitcnt vmcnt(6)
	v_lshl_add_u64 v[180:181], v[172:173], 0, s[24:25]
	s_or_b32 s24, s27, 1
	s_mov_b64 s[36:37], 0x40000
	s_mov_b64 s[42:43], 0x60000
	s_cmp_lt_u32 s24, s30
	v_lshl_add_u64 v[176:177], v[170:171], 0, s[36:37]
	s_waitcnt vmcnt(4)
	v_lshl_add_u64 v[178:179], v[170:171], 0, s[42:43]
	v_lshl_add_u64 v[182:183], v[172:173], 0, s[36:37]
	v_lshl_add_u64 v[184:185], v[172:173], 0, s[42:43]
	s_cselect_b32 s24, s24, s27
	v_lshl_add_u64 v[0:1], v[170:171], 0, s[96:97]
	v_lshl_add_u64 v[4:5], v[174:175], 0, s[96:97]
	v_lshl_add_u64 v[8:9], v[176:177], 0, s[96:97]
	v_lshl_add_u64 v[12:13], v[178:179], 0, s[96:97]
	v_lshl_add_u64 v[16:17], v[172:173], 0, s[96:97]
	v_lshl_add_u64 v[20:21], v[180:181], 0, s[96:97]
	v_lshl_add_u64 v[24:25], v[182:183], 0, s[96:97]
	v_lshl_add_u64 v[28:29], v[184:185], 0, s[96:97]
	s_lshl_b32 s96, s24, 7
	v_lshl_add_u64 v[32:33], v[170:171], 0, s[96:97]
	global_load_dwordx4 v[0:3], v[0:1], off
	s_nop 0
	global_load_dwordx4 v[4:7], v[4:5], off
	s_nop 0
	global_load_dwordx4 v[8:11], v[8:9], off
	s_nop 0
	global_load_dwordx4 v[12:15], v[12:13], off
	s_nop 0
	global_load_dwordx4 v[16:19], v[16:17], off
	s_nop 0
	global_load_dwordx4 v[20:23], v[20:21], off
	s_nop 0
	global_load_dwordx4 v[24:27], v[24:25], off
	s_nop 0
	global_load_dwordx4 v[28:31], v[28:29], off
	v_lshl_add_u64 v[34:35], v[174:175], 0, s[96:97]
	v_lshl_add_u64 v[36:37], v[176:177], 0, s[96:97]
	v_lshl_add_u64 v[38:39], v[178:179], 0, s[96:97]
	v_lshl_add_u64 v[40:41], v[172:173], 0, s[96:97]
	v_lshl_add_u64 v[42:43], v[180:181], 0, s[96:97]
	v_lshl_add_u64 v[44:45], v[182:183], 0, s[96:97]
	v_lshl_add_u64 v[46:47], v[184:185], 0, s[96:97]
	global_load_dwordx4 v[158:161], v[32:33], off
	global_load_dwordx4 v[154:157], v[34:35], off
	global_load_dwordx4 v[150:153], v[36:37], off
	global_load_dwordx4 v[146:149], v[38:39], off
	global_load_dwordx4 v[142:145], v[40:41], off
	global_load_dwordx4 v[136:139], v[42:43], off
	global_load_dwordx4 v[132:135], v[44:45], off
	global_load_dwordx4 v[128:131], v[46:47], off
	v_mov_b32_e32 v127, 0
	s_mov_b64 s[16:17], 0x20000
	s_mov_b64 s[18:19], 0x40000
	s_mov_b64 s[10:11], 0x60000
	v_mov_b32_e32 v126, v127
	v_mov_b32_e32 v125, v127
	v_mov_b32_e32 v124, v127
	v_mov_b32_e32 v123, v127
	v_mov_b32_e32 v122, v127
	v_mov_b32_e32 v121, v127
	v_mov_b32_e32 v120, v127
	v_mov_b32_e32 v119, v127
	v_mov_b32_e32 v118, v127
	v_mov_b32_e32 v117, v127
	v_mov_b32_e32 v116, v127
	v_mov_b32_e32 v115, v127
	v_mov_b32_e32 v114, v127
	v_mov_b32_e32 v113, v127
	v_mov_b32_e32 v112, v127
	v_mov_b32_e32 v111, v127
	v_mov_b32_e32 v110, v127
	v_mov_b32_e32 v109, v127
	s_cmp_ge_u32 s27, s30
	v_mov_b32_e32 v108, v127
	v_mov_b32_e32 v107, v127
	v_mov_b32_e32 v106, v127
	s_waitcnt vmcnt(19)
	v_mov_b32_e32 v105, v127
	s_waitcnt vmcnt(18)
	v_mov_b32_e32 v104, v127
	s_waitcnt vmcnt(17)
	v_mov_b32_e32 v103, v127
	s_waitcnt vmcnt(16)
	v_mov_b32_e32 v102, v127
	v_mov_b32_e32 v101, v127
	v_mov_b32_e32 v100, v127
	v_mov_b32_e32 v99, v127
	v_mov_b32_e32 v98, v127
	v_mov_b32_e32 v97, v127
	v_mov_b32_e32 v96, v127
	v_mov_b32_e32 v95, v127
	v_mov_b32_e32 v94, v127
	v_mov_b32_e32 v93, v127
	s_waitcnt vmcnt(15)
	ds_write_b128 v188, v[0:3]
	s_waitcnt vmcnt(11)
	ds_write_b128 v188, v[16:19] offset:36864
	ds_write_b128 v188, v[4:7] offset:9216
	ds_write_b128 v188, v[8:11] offset:18432
	ds_write_b128 v188, v[12:15] offset:27648
	s_waitcnt vmcnt(10)
	ds_write_b128 v188, v[20:23] offset:46080
	s_waitcnt vmcnt(9)
	ds_write_b128 v188, v[24:27] offset:55296
	s_waitcnt vmcnt(8)
; #define SSTOREG(buf_) do { char* b_ = (buf_) + lo; \
;       *(uint4*)(b_) = ra0; *(uint4*)(b_ + 64 * GSTR) = ra1; *(uint4*)(b_ + 128 * GSTR) = ra2; *(uint4*)(b_ + 192 * GSTR) = ra3; \
;       *(uint4*)(b_ + 256 * GSTR) = rw0; *(uint4*)(b_ + 320 * GSTR) = rw1; \
;       if (WM == 2) { *(uint4*)(b_ + 384 * GSTR) = rw2; *(uint4*)(b_ + 448 * GSTR) = rw3; } } while (0)
; #define SSTOREG(buf_) do { char* b_ = (buf_) + lo; \
;       *(uint4*)(b_) = ra0; *(uint4*)(b_ + 64 * GSTR) = ra1; *(uint4*)(b_ + 128 * GSTR) = ra2; *(uint4*)(b_ + 192 * GSTR) = ra3; \
;       *(uint4*)(b_ + 256 * GSTR) = rw0; *(uint4*)(b_ + 320 * GSTR) = rw1; \
;       if (WM == 2) { *(uint4*)(b_ + 384 * GSTR) = rw2; *(uint4*)(b_ + 448 * GSTR) = rw3; } } while (0)
;     ...
;     f32x16 acc[WM][4];
; #pragma unroll
;     for (int mi = 0; mi < WM; ++mi)
; #pragma unroll
;       for (int nb = 0; nb < 4; ++nb)
; #pragma unroll
;         for (int i = 0; i < 16; ++i) acc[mi][nb][i] = 0.f;
;     uint4 ra0, ra1, ra2, ra3, rw0, rw1, rw2, rw3;
;     rw2 = make_uint4(0, 0, 0, 0); rw3 = rw2;
;     const int grow = tid >> 3, gcol = (tid & 7) * 8;
;     const bf16_t* ap = Ag + (size_t)grow * K + gcol;
;     const bf16_t* wp = Wg + (size_t)grow * K + gcol;
;     const int lo = grow * GSTR + (tid & 7) * 16;
;     ...
;     GLOADG(kt0); SSTOREG(smem);
;     if (WM == 2) GLOADG(kt0 + 1 < kt1 ? kt0 + 1 : kt0);
;     __syncthreads();
;     for (int kt = kt0; kt < kt1; ++kt) {
	ds_write_b128 v188, v[28:31] offset:64512
	v_mov_b32_e32 v92, v127
	v_mov_b32_e32 v91, v127
	v_mov_b32_e32 v90, v127
	v_mov_b32_e32 v89, v127
	v_mov_b32_e32 v88, v127
	v_mov_b32_e32 v87, v127
	v_mov_b32_e32 v86, v127
	v_mov_b32_e32 v85, v127
	v_mov_b32_e32 v84, v127
	v_mov_b32_e32 v83, v127
	v_mov_b32_e32 v82, v127
	v_mov_b32_e32 v81, v127
	v_mov_b32_e32 v80, v127
	v_mov_b32_e32 v79, v127
	v_mov_b32_e32 v78, v127
	v_mov_b32_e32 v77, v127
	v_mov_b32_e32 v76, v127
	v_mov_b32_e32 v75, v127
	v_mov_b32_e32 v74, v127
	v_mov_b32_e32 v73, v127
	v_mov_b32_e32 v72, v127
	v_mov_b32_e32 v71, v127
	v_mov_b32_e32 v70, v127
	v_mov_b32_e32 v69, v127
	v_mov_b32_e32 v68, v127
	v_mov_b32_e32 v67, v127
	v_mov_b32_e32 v66, v127
	v_mov_b32_e32 v65, v127
	v_mov_b32_e32 v64, v127
	v_mov_b32_e32 v63, v127
	v_mov_b32_e32 v62, v127
	v_mov_b32_e32 v61, v127
	v_mov_b32_e32 v60, v127
	v_mov_b32_e32 v59, v127
	v_mov_b32_e32 v58, v127
	v_mov_b32_e32 v57, v127
	v_mov_b32_e32 v56, v127
	v_mov_b32_e32 v55, v127
	v_mov_b32_e32 v54, v127
	v_mov_b32_e32 v53, v127
	v_mov_b32_e32 v52, v127
	v_mov_b32_e32 v51, v127
	v_mov_b32_e32 v50, v127
	v_mov_b32_e32 v49, v127
	v_mov_b32_e32 v48, v127
	v_mov_b32_e32 v47, v127
	v_mov_b32_e32 v46, v127
	v_mov_b32_e32 v45, v127
	v_mov_b32_e32 v44, v127
	v_mov_b32_e32 v43, v127
	v_mov_b32_e32 v42, v127
	v_mov_b32_e32 v41, v127
	v_mov_b32_e32 v40, v127
	v_mov_b32_e32 v39, v127
	v_mov_b32_e32 v38, v127
	v_mov_b32_e32 v37, v127
	v_mov_b32_e32 v36, v127
	v_mov_b32_e32 v35, v127
	v_mov_b32_e32 v34, v127
	v_mov_b32_e32 v33, v127
	v_mov_b32_e32 v32, v127
	v_mov_b32_e32 v31, v127
	v_mov_b32_e32 v30, v127
	v_mov_b32_e32 v29, v127
	v_mov_b32_e32 v28, v127
	v_mov_b32_e32 v27, v127
	v_mov_b32_e32 v26, v127
	v_mov_b32_e32 v25, v127
	v_mov_b32_e32 v24, v127
	v_mov_b32_e32 v23, v127
	v_mov_b32_e32 v22, v127
	v_mov_b32_e32 v21, v127
	v_mov_b32_e32 v20, v127
	v_mov_b32_e32 v19, v127
	v_mov_b32_e32 v18, v127
	v_mov_b32_e32 v17, v127
	v_mov_b32_e32 v16, v127
	v_mov_b32_e32 v15, v127
	v_mov_b32_e32 v14, v127
	v_mov_b32_e32 v13, v127
	v_mov_b32_e32 v12, v127
	v_mov_b32_e32 v11, v127
	v_mov_b32_e32 v10, v127
	v_mov_b32_e32 v9, v127
	v_mov_b32_e32 v8, v127
	v_mov_b32_e32 v7, v127
	v_mov_b32_e32 v6, v127
	v_mov_b32_e32 v5, v127
	v_mov_b32_e32 v4, v127
	v_mov_b32_e32 v3, v127
	v_mov_b32_e32 v2, v127
	v_mov_b32_e32 v1, v127
	v_mov_b32_e32 v0, v127
	s_waitcnt lgkmcnt(0)
	s_barrier
	s_cbranch_scc1 .LBB0_103
	v_mov_b32_e32 v0, 0
	v_mov_b32_e32 v1, v0
	v_mov_b32_e32 v2, v0
	v_mov_b32_e32 v3, v0
	v_mov_b32_e32 v4, v0
	v_mov_b32_e32 v5, v0
	v_mov_b32_e32 v6, v0
	v_mov_b32_e32 v7, v0
	v_mov_b32_e32 v8, v0
	v_mov_b32_e32 v9, v0
	v_mov_b32_e32 v10, v0
	v_mov_b32_e32 v11, v0
	v_mov_b32_e32 v12, v0
	v_mov_b32_e32 v13, v0
	v_mov_b32_e32 v14, v0
	v_mov_b32_e32 v15, v0
	v_mov_b32_e32 v16, v0
	v_mov_b32_e32 v17, v0
	v_mov_b32_e32 v18, v0
	v_mov_b32_e32 v19, v0
	v_mov_b32_e32 v20, v0
	v_mov_b32_e32 v21, v0
	v_mov_b32_e32 v22, v0
	v_mov_b32_e32 v23, v0
	v_mov_b32_e32 v24, v0
	v_mov_b32_e32 v25, v0
	v_mov_b32_e32 v26, v0
	v_mov_b32_e32 v27, v0
	v_mov_b32_e32 v28, v0
	v_mov_b32_e32 v29, v0
	v_mov_b32_e32 v30, v0
	v_mov_b32_e32 v31, v0
	v_mov_b32_e32 v32, v0
	v_mov_b32_e32 v33, v0
	v_mov_b32_e32 v34, v0
	v_mov_b32_e32 v35, v0
	v_mov_b32_e32 v36, v0
	v_mov_b32_e32 v37, v0
	v_mov_b32_e32 v38, v0
	v_mov_b32_e32 v39, v0
	v_mov_b32_e32 v40, v0
	v_mov_b32_e32 v41, v0
	v_mov_b32_e32 v42, v0
	v_mov_b32_e32 v43, v0
	v_mov_b32_e32 v44, v0
	v_mov_b32_e32 v45, v0
	v_mov_b32_e32 v46, v0
	v_mov_b32_e32 v47, v0
	v_mov_b32_e32 v48, v0
	v_mov_b32_e32 v49, v0
	v_mov_b32_e32 v50, v0
	v_mov_b32_e32 v51, v0
	v_mov_b32_e32 v52, v0
	v_mov_b32_e32 v53, v0
	v_mov_b32_e32 v54, v0
	v_mov_b32_e32 v55, v0
	v_mov_b32_e32 v56, v0
	v_mov_b32_e32 v57, v0
	v_mov_b32_e32 v58, v0
	v_mov_b32_e32 v59, v0
	v_mov_b32_e32 v60, v0
	v_mov_b32_e32 v61, v0
	v_mov_b32_e32 v62, v0
	v_mov_b32_e32 v63, v0
	v_mov_b32_e32 v64, v0
	v_mov_b32_e32 v65, v0
	v_mov_b32_e32 v66, v0
	v_mov_b32_e32 v67, v0
	v_mov_b32_e32 v68, v0
	v_mov_b32_e32 v69, v0
	v_mov_b32_e32 v70, v0
	v_mov_b32_e32 v71, v0
	v_mov_b32_e32 v72, v0
	v_mov_b32_e32 v73, v0
	v_mov_b32_e32 v74, v0
	v_mov_b32_e32 v75, v0
	v_mov_b32_e32 v76, v0
	v_mov_b32_e32 v77, v0
	v_mov_b32_e32 v78, v0
	v_mov_b32_e32 v79, v0
	v_mov_b32_e32 v80, v0
	v_mov_b32_e32 v81, v0
	v_mov_b32_e32 v82, v0
	v_mov_b32_e32 v83, v0
	v_mov_b32_e32 v84, v0
	v_mov_b32_e32 v85, v0
	v_mov_b32_e32 v86, v0
	v_mov_b32_e32 v87, v0
	v_mov_b32_e32 v88, v0
	v_mov_b32_e32 v89, v0
	v_mov_b32_e32 v90, v0
	v_mov_b32_e32 v91, v0
	v_mov_b32_e32 v92, v0
	v_mov_b32_e32 v93, v0
	v_mov_b32_e32 v94, v0
	v_mov_b32_e32 v95, v0
	v_mov_b32_e32 v96, v0
	v_mov_b32_e32 v97, v0
	v_mov_b32_e32 v98, v0
	v_mov_b32_e32 v99, v0
	v_mov_b32_e32 v100, v0
	v_mov_b32_e32 v101, v0
	v_mov_b32_e32 v102, v0
	v_mov_b32_e32 v103, v0
	v_mov_b32_e32 v104, v0
	v_mov_b32_e32 v105, v0
	v_mov_b32_e32 v106, v0
	v_mov_b32_e32 v107, v0
	v_mov_b32_e32 v108, v0
	v_mov_b32_e32 v109, v0
	v_mov_b32_e32 v110, v0
	v_mov_b32_e32 v111, v0
	v_mov_b32_e32 v112, v0
	v_mov_b32_e32 v113, v0
	v_mov_b32_e32 v114, v0
	v_mov_b32_e32 v115, v0
	v_mov_b32_e32 v116, v0
	v_mov_b32_e32 v117, v0
	v_mov_b32_e32 v118, v0
	v_mov_b32_e32 v119, v0
	v_mov_b32_e32 v120, v0
	v_mov_b32_e32 v121, v0
	v_mov_b32_e32 v122, v0
	v_mov_b32_e32 v123, v0
	v_mov_b32_e32 v124, v0
	v_mov_b32_e32 v125, v0
	v_mov_b32_e32 v126, v0
	v_mov_b32_e32 v127, v0
